# W2(no-stats) K-loop saddr addressing, ret_c q-load hoist, no grid barrier between independent phases 22 and 23
# speedup vs baseline: 1.0013x; 1.0013x over previous
; #define LAS __attribute__((address_space(3)))
; __device__ __forceinline__ u32x4 mk4(unsigned a, unsigned b, unsigned c, unsigned d) { return (u32x4){a, b, c, d}; }
; __device__ __forceinline__ int otid() { int t = threadIdx.x; asm volatile("" : "+v"(t)); return t; }
; __device__ void ret_c_unit(CP P, int hf, int unit, LAS unsigned char* lds) {
;     const int rh = (unit >> 3) & 1, ur = (unit & 7) | ((unit >> 4) << 3), sc = ur & 31, h = (ur >> 5) & 7, bl = ur >> 8;
;     const bf16_t* PR = (const bf16_t*)(P->ws + OFF_PROJ1); const bf16_t* RST = (const bf16_t*)(P->ws + OFF_RST);
;     const float* cs = (const float*)(P->ws + OFF_ROPE); const float* sn = cs + 8192 * 64;
;     const int tid = otid(), lane = tid & 63, wid = tid >> 6;
;     const size_t r0 = (size_t)bl * 8192 + sc * 256;
;     const float lgf = ret_lg(h), lgb = ret_lg(7 - h);
;     LAS bf16_t* qs = (LAS bf16_t*)lds;
;     LAS bf16_t* ks = (LAS bf16_t*)(lds + 34816);
;     LAS bf16_t* Ps = (LAS bf16_t*)(lds + 52224);
;     LAS bf16_t* Vs = (LAS bf16_t*)(lds + 70656);
;     LAS float* red = (LAS float*)(lds + 104448);
;     LAS bf16_t* qx = ks;
; #pragma unroll
;     for (int rep = 0; rep < 2; ++rep) { const int i = (tid >> 3) + rep * 64, dq = (tid & 7) * 8, I = rh * 128 + i;
;         const KRaw q_ = rot_load(PR + (r0 + I) * 6144 + h * 128, nullptr, nullptr, dq);
;         *(LAS u32x4*)(qs + i * 136 + dq) = mk4(q_.a.x, q_.a.y, q_.a.z, q_.a.w); *(LAS u32x4*)(qs + i * 136 + 64 + dq) = mk4(q_.b.x, q_.b.y, q_.b.z, q_.b.w); }
.LBB0_245:
	s_lshr_b32 s11, s18, 1
	s_and_b32 s10, s18, 7
	s_and_b32 s11, s11, 24
	s_ashr_i32 s86, s18, 9
	s_or_b32 s23, s11, s10
	s_ashr_i32 s87, s86, 31
	s_lshl_b64 s[36:37], s[86:87], 13
	s_lshl_b32 s11, s23, 8
	s_bfe_u32 s10, s18, 0x30006
	s_or_b32 s36, s36, s11
	s_cmp_eq_u32 s10, 1
	s_cselect_b64 vcc, -1, 0
	s_cmp_eq_u32 s10, 2
	s_cselect_b64 s[40:41], -1, 0
	s_cmp_eq_u32 s10, 3
	s_cselect_b64 s[42:43], -1, 0
	s_cmp_eq_u32 s10, 4
	s_cselect_b64 s[44:45], -1, 0
	s_cmp_eq_u32 s10, 5
	s_cselect_b64 s[46:47], -1, 0
	s_cmp_eq_u32 s10, 6
	v_mov_b32_e32 v170, v191
	s_cselect_b64 s[48:49], -1, 0
	s_lshl_b32 s11, s18, 4
	s_and_b32 s19, s11, 0x80
	v_ashrrev_i32_e32 v0, 3, v170
	s_lshl_b32 s66, s10, 8
	s_add_u32 s12, s14, s66
	v_add_u32_e32 v6, s19, v0
	s_addc_u32 s13, s15, 0
	v_ashrrev_i32_e32 v7, 31, v6
	v_lshl_add_u64 v[2:3], s[36:37], 0, v[6:7]
	v_mov_b64_e32 v[14:15], s[12:13]
	v_mad_u64_u32 v[4:5], s[12:13], v2, s24, v[14:15]
	v_lshlrev_b32_e32 v1, 4, v170
	v_mad_i32_i24 v5, v3, s24, v5
	v_and_b32_e32 v16, 0x70, v1
	v_mov_b32_e32 v17, v184
	v_lshl_add_u64 v[8:9], v[4:5], 0, v[16:17]
	global_load_dwordx4 v[2:5], v[8:9], off
	global_load_dwordx4 v[10:13], v[8:9], off offset:128
	v_add_u32_e32 v20, 64, v6
	v_ashrrev_i32_e32 v21, 31, v20
	v_lshl_add_u64 v[20:21], s[36:37], 0, v[20:21]
	v_mad_u64_u32 v[22:23], s[12:13], v20, s24, v[14:15]
	v_mad_i32_i24 v23, v21, s24, v23
	v_lshl_add_u64 v[20:21], v[22:23], 0, v[16:17]
	global_load_dwordx4 v[24:27], v[20:21], off
	global_load_dwordx4 v[28:31], v[20:21], off offset:128
	v_mul_lo_u32 v1, v0, s25
	v_add_u32_e32 v8, 0, v1
	v_add_u32_e32 v1, v8, v16
	s_cmp_lg_u32 s10, 7
	v_mov_b32_e32 v18, 0xb9800400
	s_mov_b32 s21, s67
	v_and_b32_e32 v104, 15, v170
	v_ashrrev_i32_e32 v173, 8, v170
	v_lshlrev_b32_e32 v172, 3, v170
	v_mov_b64_e32 v[196:197], 0x200
	v_mov_b32_e32 v230, 0xbb00200b
	v_mov_b32_e32 v190, 0xba801003
	v_mov_b32_e32 v229, 0xba000801
	s_mov_b32 s11, 0
	v_and_b32_e32 v180, 63, v170
	v_mov_b32_e32 v240, 0xb9800400
	s_waitcnt vmcnt(2)
	ds_write_b128 v1, v[2:5]
	s_waitcnt vmcnt(2)
	ds_write_b128 v1, v[10:13] offset:128
	v_mov_b64_e32 v[6:7], s[14:15]
	v_and_b32_e32 v17, 7, v170
	v_lshrrev_b32_e32 v16, 5, v170
	v_and_b32_e32 v179, 6, v16
	v_lshlrev_b32_e32 v108, 4, v179
	v_or_b32_e32 v175, v108, v104
	v_or_b32_e32 v178, 1, v179
	v_lshlrev_b32_e32 v100, 4, v178
	v_or_b32_e32 v177, s19, v175
	v_or_b32_e32 v174, v100, v104
	v_mul_u32_u24_e32 v119, 0x90, v175
	v_mul_u32_u24_e32 v120, 0x90, v174
	s_waitcnt vmcnt(1)
	ds_write_b128 v1, v[24:27] offset:17408
	s_waitcnt vmcnt(0)
; #define LAS __attribute__((address_space(3)))
; __device__ __forceinline__ u32x4 mk4(unsigned a, unsigned b, unsigned c, unsigned d) { return (u32x4){a, b, c, d}; }
; __device__ void ret_c_unit(CP P, int hf, int unit, LAS unsigned char* lds) {
;     ...
;         *(LAS u32x4*)(qs + i * 136 + dq) = mk4(q_.a.x, q_.a.y, q_.a.z, q_.a.w); *(LAS u32x4*)(qs + i * 136 + 64 + dq) = mk4(q_.b.x, q_.b.y, q_.b.z, q_.b.w); }
;     f32x4 acc[2][8];
; #pragma unroll
;     for (int r = 0; r < 2; ++r)
; #pragma unroll
;         for (int n = 0; n < 8; ++n) acc[r][n] = (f32x4){0.f, 0.f, 0.f, 0.f};
;     const int mi2 = (wid & 3) * 2, nb = (wid >> 2) * 8;
;     const int pj = tid >> 3, pdq = (tid & 7) * 8, pv32 = (tid & 7) * 32;
;     const bf16_t* kbase = PR + (r0 + pj) * 6144 + 1024 + h * 128; const bf16_t* vbase = PR + (r0 + pj) * 6144 + 2048 + h * 256 + pv32;
;     KRaw kr = rot_load(kbase, cs + (sc * 256 + pj) * 64, sn + (sc * 256 + pj) * 64, pdq);
;     uint4 vr[4];
; #pragma unroll
;     for (int hh = 0; hh < 4; ++hh) vr[hh] = *(const uint4*)(vbase + hh * 8);
;     uint4 st[4];
;     const bf16_t* sbase = RST + ((size_t)((bl * 8 + h) * 2) * 32 + sc) * 32768;
	ds_write_b128 v1, v[28:31] offset:17536
	v_cndmask_b32_e32 v1, v238, v239, vcc
	v_cndmask_b32_e64 v2, v238, v239, s[48:49]
	v_cndmask_b32_e64 v1, v1, v249, s[40:41]
	v_cndmask_b32_e64 v2, v2, v249, s[46:47]
	v_cndmask_b32_e64 v1, v1, v232, s[42:43]
	v_cndmask_b32_e64 v2, v2, v232, s[44:45]
	v_cndmask_b32_e64 v1, v1, v233, s[44:45]
	v_cndmask_b32_e64 v2, v2, v233, s[42:43]
	v_cndmask_b32_e64 v1, v1, v248, s[46:47]
	v_cndmask_b32_e64 v2, v2, v248, s[40:41]
	v_cndmask_b32_e64 v1, v1, v250, s[48:49]
	v_cndmask_b32_e32 v9, v2, v250, vcc
	s_cselect_b64 vcc, -1, 0
	v_cndmask_b32_e32 v166, v18, v1, vcc
	v_ashrrev_i32_e32 v1, 31, v0
	v_lshl_add_u64 v[4:5], s[36:37], 0, v[0:1]
	v_mad_u64_u32 v[6:7], s[12:13], v4, s24, v[6:7]
	v_mad_u64_u32 v[2:3], s[12:13], v4, s24, 0
	v_mad_i32_i24 v7, v5, s24, v7
	s_lshl_b32 s20, s10, 9
	v_mad_i32_i24 v1, v5, s24, v3
	v_lshl_add_u64 v[10:11], v[6:7], 0, s[66:67]
	v_lshl_add_u64 v[6:7], v[6:7], 0, s[20:21]
	v_lshlrev_b32_e32 v4, 6, v17
	v_mov_b32_e32 v5, v184
	v_lshl_add_u64 v[12:13], v[6:7], 0, v[4:5]
	v_lshlrev_b32_e32 v6, 4, v17
	v_mov_b32_e32 v7, v184
	v_lshl_add_u64 v[10:11], v[10:11], 0, v[6:7]
	global_load_dwordx4 v[68:71], v[10:11], off offset:2048
	global_load_dwordx4 v[64:67], v[10:11], off offset:2176
	v_add_co_u32_e32 v10, vcc, s17, v12
	v_lshl_add_u64 v[14:15], v[12:13], 0, s[54:55]
	s_nop 0
	v_addc_co_u32_e32 v11, vcc, 0, v13, vcc
	global_load_dwordx4 v[84:87], v[10:11], off
	global_load_dwordx4 v[72:75], v[14:15], off offset:48
	global_load_dwordx4 v[76:79], v[14:15], off offset:32
	global_load_dwordx4 v[80:83], v[14:15], off offset:16
	s_movk_i32 s12, 0x210
	s_cmp_lg_u32 s10, 0
	v_add_u32_e32 v118, v8, v6
	v_mul_lo_u32 v0, v0, s12
	v_lshrrev_b32_e32 v7, 1, v170
	v_lshrrev_b32_e32 v8, 2, v170
	s_cselect_b64 vcc, -1, 0
	v_add3_u32 v117, s16, v0, v4
	v_lshlrev_b32_e32 v0, 5, v173
	v_and_b32_e32 v7, 24, v7
	v_and_b32_e32 v176, 12, v8
	v_cndmask_b32_e32 v207, v18, v9, vcc
	v_lshlrev_b32_e32 v3, 3, v173
	v_lshl_add_u32 v208, v7, 1, 0
	v_and_or_b32 v7, v8, 3, v7
	v_or_b32_e32 v115, v0, v176
	v_sub_u32_e32 v18, v177, v176
	v_mul_u32_u24_e32 v5, 0x88, v104
	v_mul_u32_u24_e32 v7, 0x210, v7
	v_and_b32_e32 v8, 24, v172
	v_lshlrev_b32_e32 v10, 1, v115
	v_or_b32_e32 v116, 16, v0
	v_or_b32_e32 v105, 1, v3
	v_or_b32_e32 v103, 2, v3
	v_or_b32_e32 v102, 3, v3
	v_or_b32_e32 v110, 4, v3
	v_or_b32_e32 v107, 5, v3
	v_or_b32_e32 v106, 6, v3
	v_or_b32_e32 v101, 7, v3
	v_sub_u32_e32 v121, v18, v0
	v_or3_b32 v0, v2, s20, v4
	v_lshl_add_u32 v5, v5, 1, v208
	v_add3_u32 v7, s16, v7, v8
	v_mul_u32_u24_e32 v8, 0x1100, v179
	v_mul_i32_i24_e32 v9, 0x2200, v173
	v_add3_u32 v114, 0, v119, v10
	v_mul_lo_u32 v11, v116, s25
	v_add3_u32 v109, 0, v120, v10
	v_and_b32_e32 v10, 0xffffff00, v170
	v_lshlrev_b32_e32 v12, 5, v105
	v_lshlrev_b32_e32 v13, 5, v103
	v_lshlrev_b32_e32 v14, 5, v102
	v_lshlrev_b32_e32 v15, 5, v110
	v_lshlrev_b32_e32 v16, 5, v107
	v_lshlrev_b32_e32 v17, 5, v106
	v_lshlrev_b32_e32 v3, 5, v101
	v_lshl_add_u64 v[96:97], s[56:57], 0, v[0:1]
	v_or3_b32 v0, v2, s66, v6
	v_mov_b32_e32 v4, 0
	v_lshl_add_u64 v[98:99], s[82:83], 0, v[0:1]
	v_add_u32_e32 v112, v5, v8
	v_add_u32_e32 v113, v5, v9
	v_add_u32_e32 v111, v5, v11
	v_add_u32_e32 v206, v7, v10
	v_add_u32_e32 v205, v7, v12
	v_add_u32_e32 v204, v7, v13
	v_add_u32_e32 v203, v7, v14
	v_add_u32_e32 v202, v7, v15
	v_add_u32_e32 v183, v7, v16
	v_add_u32_e32 v182, v7, v17
	v_add_u32_e32 v181, v7, v3
	v_mov_b32_e32 v5, v4
	v_mov_b32_e32 v6, v4
	v_mov_b32_e32 v7, v4
	v_mov_b32_e32 v8, v4
	v_mov_b32_e32 v9, v4
	v_mov_b32_e32 v10, v4
	v_mov_b32_e32 v11, v4
	v_mov_b32_e32 v12, v4
	v_mov_b32_e32 v13, v4
	v_mov_b32_e32 v14, v4
	v_mov_b32_e32 v15, v4
	v_mov_b32_e32 v16, v4
	v_mov_b32_e32 v17, v4
	v_mov_b32_e32 v18, v4
	v_mov_b32_e32 v19, v4
	v_mov_b32_e32 v20, v4
	v_mov_b32_e32 v21, v4
	v_mov_b32_e32 v22, v4
	v_mov_b32_e32 v23, v4
	v_mov_b32_e32 v24, v4
	v_mov_b32_e32 v25, v4
	v_mov_b32_e32 v26, v4
	v_mov_b32_e32 v27, v4
	v_mov_b32_e32 v28, v4
	v_mov_b32_e32 v29, v4
	v_mov_b32_e32 v30, v4
	v_mov_b32_e32 v31, v4
	v_mov_b32_e32 v32, v4
	v_mov_b32_e32 v33, v4
	v_mov_b32_e32 v34, v4
	v_mov_b32_e32 v35, v4
	v_mov_b32_e32 v36, v4
	v_mov_b32_e32 v37, v4
	v_mov_b32_e32 v38, v4
	v_mov_b32_e32 v39, v4
	v_mov_b32_e32 v40, v4
	v_mov_b32_e32 v41, v4
	v_mov_b32_e32 v42, v4
	v_mov_b32_e32 v43, v4
	v_mov_b32_e32 v44, v4
	v_mov_b32_e32 v45, v4
	v_mov_b32_e32 v46, v4
	v_mov_b32_e32 v47, v4
	v_mov_b32_e32 v48, v4
	v_mov_b32_e32 v49, v4
	v_mov_b32_e32 v50, v4
	v_mov_b32_e32 v51, v4
	v_mov_b32_e32 v52, v4
	v_mov_b32_e32 v53, v4
	v_mov_b32_e32 v54, v4
	v_mov_b32_e32 v55, v4
	v_mov_b32_e32 v56, v4
	v_mov_b32_e32 v57, v4
	v_mov_b32_e32 v58, v4
	v_mov_b32_e32 v59, v4
	v_mov_b32_e32 v60, v4
	v_mov_b32_e32 v61, v4
	v_mov_b32_e32 v62, v4
	v_mov_b32_e32 v63, v4
	v_mov_b32_e32 v0, v4
	v_mov_b32_e32 v1, v4
	v_mov_b32_e32 v2, v4
	v_mov_b32_e32 v3, v4
	s_mov_b64 s[12:13], 0xc0000

; #define PG8_STAGE(bufoff, gbase, voff) do { _Pragma("unroll") for (int _i = 0; _i < 2; ++_i) \
;         __builtin_amdgcn_global_load_lds((const unsigned*)((const char*)(gbase) + (voff)[_i]), (LAS unsigned*)(lds + (bufoff) + ldsw + _i * 8192), 16, 0, 0); } while (0)
; #define PG8_LDA(dst, b, h) do { _Pragma("unroll") for (int m = 0; m < 4; ++m) _Pragma("unroll") for (int k = 0; k < 2; ++k) dst[m][k] = *(const LAS bf16x8*)(lds + PG8_SA(b, h) + aoff + m * 2048 + k * 1024); } while (0)
; #define PG8_LDB(dst, b, h) do { _Pragma("unroll") for (int n = 0; n < 2; ++n) _Pragma("unroll") for (int k = 0; k < 2; ++k) dst[n][k] = *(const LAS bf16x8*)(lds + PG8_SB(b, h) + boff + n * 2048 + k * 1024); } while (0)
; #define PG8_MMA(ai, bj, At, Bt) do { __builtin_amdgcn_s_setprio(1); _Pragma("unroll") for (int m = 0; m < 4; ++m) _Pragma("unroll") for (int n = 0; n < 2; ++n) _Pragma("unroll") for (int k = 0; k < 2; ++k) \
;         acc[ai][bj][m][n] = __builtin_amdgcn_mfma_f32_16x16x32_bf16(Bt[n][k], At[m][k], acc[ai][bj][m][n], 0, 0, 0); __builtin_amdgcn_s_setprio(0); } while (0)
; #define PG8_WAIT_V(n) asm volatile("s_waitcnt vmcnt(" #n ")" ::: "memory")
; #define PG8_WAIT_L(n) asm volatile("s_waitcnt lgkmcnt(" #n ")" ::: "memory")
; #define PG8_BAR __builtin_amdgcn_s_barrier()
; #define PG8_SCHED __builtin_amdgcn_sched_barrier(0)
; template <class Epi>
; __device__ __forceinline__ void gemm_phase(LAS unsigned char* lds, const Gemm g, const Epi& E) {
;     ...
;         for (int t = 0; t < nt; t += 2) {
;             const bool last = (t == nt - 2);
;             const char* a1 = cA + (size_t)(t + 1) * kstep;
;             const char* a2 = last ? nA : cA + (size_t)(t + 2) * kstep; const char* b2 = last ? nB : cB + (size_t)(t + 2) * kstep;
;             const char* a3 = a2 + kstep; const char* b3 = b2 + kstep;
;             PG8_LDB(B0, 0, 0); PG8_LDB(B1, 0, 1); PG8_SCHED; PG8_LDA(At, 0, 0); PG8_STAGE(PG8_SA(1, 1), a1 + hstepA, voffA);
;             PG8_WAIT_V(8); PG8_WAIT_L(0); PG8_BAR; PG8_MMA(0, 0, At, B0); PG8_MMA(0, 1, At, B1); PG8_BAR; PG8_SCHED;
;     ...
; #pragma unroll
;         for (int a = 0; a < 2; ++a)
; #pragma unroll
;             for (int b = 0; b < 2; ++b)
; #pragma unroll
;                 for (int m = 0; m < 4; ++m)
; #pragma unroll
;                     for (int n = 0; n < 2; ++n) acc[a][b][m][n] = (f32x4){0.f, 0.f, 0.f, 0.f};
.LBB0_546:
	s_add_u32 s12, s22, 0x100
	v_mov_b32_e32 v0, 0
	s_addc_u32 s13, s23, 0
	s_mov_b32 s42, -2
	v_mov_b32_e32 v1, v0
	v_mov_b32_e32 v2, v0
	v_mov_b32_e32 v3, v0
	v_mov_b32_e32 v4, v0
	v_mov_b32_e32 v5, v0
	v_mov_b32_e32 v6, v0
	v_mov_b32_e32 v7, v0
	v_mov_b32_e32 v12, v0
	v_mov_b32_e32 v13, v0
	v_mov_b32_e32 v14, v0
	v_mov_b32_e32 v15, v0
	v_mov_b32_e32 v20, v0
	v_mov_b32_e32 v21, v0
	v_mov_b32_e32 v22, v0
	v_mov_b32_e32 v23, v0
	v_mov_b32_e32 v32, v0
	v_mov_b32_e32 v33, v0
	v_mov_b32_e32 v34, v0
	v_mov_b32_e32 v35, v0
	v_mov_b32_e32 v36, v0
	v_mov_b32_e32 v37, v0
	v_mov_b32_e32 v38, v0
	v_mov_b32_e32 v39, v0
	v_mov_b32_e32 v40, v0
	v_mov_b32_e32 v41, v0
	v_mov_b32_e32 v42, v0
	v_mov_b32_e32 v43, v0
	v_mov_b32_e32 v44, v0
	v_mov_b32_e32 v45, v0
	v_mov_b32_e32 v46, v0
	v_mov_b32_e32 v47, v0
	v_mov_b32_e32 v8, v0
	v_mov_b32_e32 v9, v0
	v_mov_b32_e32 v10, v0
	v_mov_b32_e32 v11, v0
	v_mov_b32_e32 v16, v0
	v_mov_b32_e32 v17, v0
	v_mov_b32_e32 v18, v0
	v_mov_b32_e32 v19, v0
	v_mov_b32_e32 v24, v0
	v_mov_b32_e32 v25, v0
	v_mov_b32_e32 v26, v0
	v_mov_b32_e32 v27, v0
	v_mov_b32_e32 v28, v0
	v_mov_b32_e32 v29, v0
	v_mov_b32_e32 v30, v0
	v_mov_b32_e32 v31, v0
	v_mov_b32_e32 v48, v0
	v_mov_b32_e32 v49, v0
	v_mov_b32_e32 v50, v0
	v_mov_b32_e32 v51, v0
	v_mov_b32_e32 v52, v0
	v_mov_b32_e32 v53, v0
	v_mov_b32_e32 v54, v0
	v_mov_b32_e32 v55, v0
	v_mov_b32_e32 v56, v0
	v_mov_b32_e32 v57, v0
	v_mov_b32_e32 v58, v0
	v_mov_b32_e32 v59, v0
	v_mov_b32_e32 v60, v0
	v_mov_b32_e32 v61, v0
	v_mov_b32_e32 v62, v0
	v_mov_b32_e32 v63, v0
	v_mov_b32_e32 v64, v0
	v_mov_b32_e32 v65, v0
	v_mov_b32_e32 v66, v0
	v_mov_b32_e32 v67, v0
	v_mov_b32_e32 v68, v0
	v_mov_b32_e32 v69, v0
	v_mov_b32_e32 v70, v0
	v_mov_b32_e32 v71, v0
	v_mov_b32_e32 v72, v0
	v_mov_b32_e32 v73, v0
	v_mov_b32_e32 v74, v0
	v_mov_b32_e32 v75, v0
	v_mov_b32_e32 v76, v0
	v_mov_b32_e32 v77, v0
	v_mov_b32_e32 v78, v0
	v_mov_b32_e32 v79, v0
	v_mov_b32_e32 v96, v0
	v_mov_b32_e32 v97, v0
	v_mov_b32_e32 v98, v0
	v_mov_b32_e32 v99, v0
	v_mov_b32_e32 v100, v0
	v_mov_b32_e32 v101, v0
	v_mov_b32_e32 v102, v0
	v_mov_b32_e32 v103, v0
	v_mov_b32_e32 v104, v0
	v_mov_b32_e32 v105, v0
	v_mov_b32_e32 v106, v0
	v_mov_b32_e32 v107, v0
	v_mov_b32_e32 v108, v0
	v_mov_b32_e32 v109, v0
	v_mov_b32_e32 v110, v0
	v_mov_b32_e32 v111, v0
	v_mov_b32_e32 v80, v0
	v_mov_b32_e32 v81, v0
	v_mov_b32_e32 v82, v0
	v_mov_b32_e32 v83, v0
	v_mov_b32_e32 v84, v0
	v_mov_b32_e32 v85, v0
	v_mov_b32_e32 v86, v0
	v_mov_b32_e32 v87, v0
	v_mov_b32_e32 v88, v0
	v_mov_b32_e32 v89, v0
	v_mov_b32_e32 v90, v0
	v_mov_b32_e32 v91, v0
	v_mov_b32_e32 v92, v0
	v_mov_b32_e32 v93, v0
	v_mov_b32_e32 v94, v0
	v_mov_b32_e32 v95, v0
	v_mov_b32_e32 v112, v0
	v_mov_b32_e32 v113, v0
	v_mov_b32_e32 v114, v0
	v_mov_b32_e32 v115, v0
	v_mov_b32_e32 v116, v0
	v_mov_b32_e32 v117, v0
	v_mov_b32_e32 v118, v0
	v_mov_b32_e32 v119, v0
	v_mov_b32_e32 v120, v0
	v_mov_b32_e32 v121, v0
	v_mov_b32_e32 v122, v0
	v_mov_b32_e32 v123, v0
	v_mov_b32_e32 v124, v0
	v_mov_b32_e32 v125, v0
	v_mov_b32_e32 v126, v0
	v_mov_b32_e32 v127, v0
	v_add_u32_e32 v186, 0x10000, v149
.LBB0_547:
	s_add_u32 s22, s20, 0x100
	s_addc_u32 s23, s21, 0
	s_cmp_eq_u32 s42, 40
	s_cselect_b32 s39, s31, s23
	s_cselect_b32 s38, s30, s22
	s_cselect_b32 s37, s35, s13
	s_cselect_b32 s36, s34, s12
	ds_read_b128 v[140:143], v186
	ds_read_b128 v[144:147], v186 offset:1024
	ds_read_b128 v[152:155], v186 offset:2048
	ds_read_b128 v[156:159], v186 offset:3072
	ds_read_b128 v[160:163], v186 offset:16384
	ds_read_b128 v[164:167], v186 offset:17408
	ds_read_b128 v[168:171], v186 offset:18432
	ds_read_b128 v[172:175], v186 offset:19456
	s_add_i32 m0, s45, 0xc000
	ds_read_b128 v[176:179], v151
	ds_read_b128 v[180:183], v151 offset:1024
	ds_read_b128 v[202:205], v151 offset:2048
	ds_read_b128 v[206:209], v151 offset:3072
	ds_read_b128 v[210:213], v151 offset:4096
	ds_read_b128 v[214:217], v151 offset:5120
	ds_read_b128 v[218:221], v151 offset:6144
	ds_read_b128 v[222:225], v151 offset:7168
	global_load_lds_dwordx4 v136, s[20:21]
	s_add_i32 m0, s45, 0xe000
	s_nop 0
	global_load_lds_dwordx4 v138, s[20:21]
	s_waitcnt vmcnt(8)
	s_waitcnt lgkmcnt(0)
	s_barrier
	s_setprio 1
	s_waitcnt lgkmcnt(0)
	v_mfma_f32_16x16x32_bf16 v[124:127], v[140:143], v[176:179], v[124:127]
	v_mfma_f32_16x16x32_bf16 v[120:123], v[152:155], v[176:179], v[120:123]
	v_mfma_f32_16x16x32_bf16 v[116:119], v[140:143], v[202:205], v[116:119]
	v_mfma_f32_16x16x32_bf16 v[112:115], v[152:155], v[202:205], v[112:115]
	v_mfma_f32_16x16x32_bf16 v[92:95], v[140:143], v[210:213], v[92:95]
	v_mfma_f32_16x16x32_bf16 v[88:91], v[152:155], v[210:213], v[88:91]
	v_mfma_f32_16x16x32_bf16 v[84:87], v[140:143], v[218:221], v[84:87]
	v_mfma_f32_16x16x32_bf16 v[80:83], v[152:155], v[218:221], v[80:83]
	v_mfma_f32_16x16x32_bf16 v[124:127], v[144:147], v[180:183], v[124:127]
	v_mfma_f32_16x16x32_bf16 v[120:123], v[156:159], v[180:183], v[120:123]
	v_mfma_f32_16x16x32_bf16 v[116:119], v[144:147], v[206:209], v[116:119]
	v_mfma_f32_16x16x32_bf16 v[112:115], v[156:159], v[206:209], v[112:115]
	v_mfma_f32_16x16x32_bf16 v[92:95], v[144:147], v[214:217], v[92:95]
	v_mfma_f32_16x16x32_bf16 v[88:91], v[156:159], v[214:217], v[88:91]
	v_mfma_f32_16x16x32_bf16 v[84:87], v[144:147], v[222:225], v[84:87]
	v_mfma_f32_16x16x32_bf16 v[80:83], v[156:159], v[222:225], v[80:83]
	v_mfma_f32_16x16x32_bf16 v[108:111], v[160:163], v[176:179], v[108:111]
	v_mfma_f32_16x16x32_bf16 v[104:107], v[168:171], v[176:179], v[104:107]
	v_mfma_f32_16x16x32_bf16 v[100:103], v[160:163], v[202:205], v[100:103]
	v_mfma_f32_16x16x32_bf16 v[96:99], v[168:171], v[202:205], v[96:99]
	v_mfma_f32_16x16x32_bf16 v[76:79], v[160:163], v[210:213], v[76:79]
	v_mfma_f32_16x16x32_bf16 v[72:75], v[168:171], v[210:213], v[72:75]
	v_mfma_f32_16x16x32_bf16 v[68:71], v[160:163], v[218:221], v[68:71]
	v_mfma_f32_16x16x32_bf16 v[64:67], v[168:171], v[218:221], v[64:67]
	v_mfma_f32_16x16x32_bf16 v[108:111], v[164:167], v[180:183], v[108:111]
	v_mfma_f32_16x16x32_bf16 v[104:107], v[172:175], v[180:183], v[104:107]
	v_mfma_f32_16x16x32_bf16 v[100:103], v[164:167], v[206:209], v[100:103]
	v_mfma_f32_16x16x32_bf16 v[96:99], v[172:175], v[206:209], v[96:99]
	v_mfma_f32_16x16x32_bf16 v[76:79], v[164:167], v[214:217], v[76:79]
	v_mfma_f32_16x16x32_bf16 v[72:75], v[172:175], v[214:217], v[72:75]
	v_mfma_f32_16x16x32_bf16 v[68:71], v[164:167], v[222:225], v[68:71]
	v_mfma_f32_16x16x32_bf16 v[64:67], v[172:175], v[222:225], v[64:67]
	s_setprio 0
	s_barrier
; #define PG8_STAGE(bufoff, gbase, voff) do { _Pragma("unroll") for (int _i = 0; _i < 2; ++_i) \
;         __builtin_amdgcn_global_load_lds((const unsigned*)((const char*)(gbase) + (voff)[_i]), (LAS unsigned*)(lds + (bufoff) + ldsw + _i * 8192), 16, 0, 0); } while (0)
; #define PG8_LDA(dst, b, h) do { _Pragma("unroll") for (int m = 0; m < 4; ++m) _Pragma("unroll") for (int k = 0; k < 2; ++k) dst[m][k] = *(const LAS bf16x8*)(lds + PG8_SA(b, h) + aoff + m * 2048 + k * 1024); } while (0)
; #define PG8_LDB(dst, b, h) do { _Pragma("unroll") for (int n = 0; n < 2; ++n) _Pragma("unroll") for (int k = 0; k < 2; ++k) dst[n][k] = *(const LAS bf16x8*)(lds + PG8_SB(b, h) + boff + n * 2048 + k * 1024); } while (0)
; #define PG8_MMA(ai, bj, At, Bt) do { __builtin_amdgcn_s_setprio(1); _Pragma("unroll") for (int m = 0; m < 4; ++m) _Pragma("unroll") for (int n = 0; n < 2; ++n) _Pragma("unroll") for (int k = 0; k < 2; ++k) \
;         acc[ai][bj][m][n] = __builtin_amdgcn_mfma_f32_16x16x32_bf16(Bt[n][k], At[m][k], acc[ai][bj][m][n], 0, 0, 0); __builtin_amdgcn_s_setprio(0); } while (0)
; #define PG8_WAIT_V(n) asm volatile("s_waitcnt vmcnt(" #n ")" ::: "memory")
; #define PG8_WAIT_L(n) asm volatile("s_waitcnt lgkmcnt(" #n ")" ::: "memory")
; #define PG8_BAR __builtin_amdgcn_s_barrier()
; #define PG8_SCHED __builtin_amdgcn_sched_barrier(0)
; template <class Epi>
; __device__ __forceinline__ void gemm_phase(LAS unsigned char* lds, const Gemm g, const Epi& E) {
;     ...
;             PG8_WAIT_V(8); PG8_WAIT_L(0); PG8_BAR; PG8_MMA(0, 0, At, B0); PG8_MMA(0, 1, At, B1); PG8_BAR; PG8_SCHED;
;             PG8_LDA(At, 0, 1); PG8_STAGE(PG8_SB(0, 0), b2, voffB); PG8_STAGE(PG8_SB(0, 1), b2 + hstepB, voffB); PG8_STAGE(PG8_SA(0, 0), a2, voffA);
;             PG8_WAIT_V(8); PG8_WAIT_L(0); PG8_BAR; PG8_MMA(1, 0, At, B0); PG8_MMA(1, 1, At, B1); PG8_BAR; PG8_SCHED;
;             PG8_LDB(B0, 1, 0); PG8_LDB(B1, 1, 1); PG8_SCHED; PG8_LDA(At, 1, 0); PG8_STAGE(PG8_SA(0, 1), a2 + hstepA, voffA);
;             PG8_WAIT_V(8); PG8_WAIT_L(0); PG8_BAR; PG8_MMA(0, 0, At, B0); PG8_MMA(0, 1, At, B1); PG8_BAR; PG8_SCHED;
	s_add_i32 s24, s44, 0x10000
	s_mov_b32 m0, s24
	ds_read_b128 v[176:179], v151 offset:16384
	ds_read_b128 v[180:183], v151 offset:17408
	ds_read_b128 v[202:205], v151 offset:18432
	ds_read_b128 v[206:209], v151 offset:19456
	ds_read_b128 v[210:213], v151 offset:20480
	ds_read_b128 v[214:217], v151 offset:21504
	ds_read_b128 v[218:221], v151 offset:22528
	ds_read_b128 v[222:225], v151 offset:23552
	global_load_lds_dwordx4 v130, s[36:37]
	s_add_i32 m0, s24, 0x2000
	s_add_u32 s20, s36, 0xb0000
	s_addc_u32 s21, s37, 0
	s_add_i32 s24, s44, 0x14000
	global_load_lds_dwordx4 v134, s[36:37]
	s_mov_b32 m0, s24
	s_nop 0
	global_load_lds_dwordx4 v130, s[20:21]
	s_add_i32 m0, s24, 0x2000
	s_nop 0
	global_load_lds_dwordx4 v134, s[20:21]
	s_mov_b32 m0, s45
	s_nop 0
	global_load_lds_dwordx4 v128, s[38:39]
	s_mov_b32 m0, s46
	s_nop 0
	global_load_lds_dwordx4 v132, s[38:39]
	s_waitcnt vmcnt(8)
	s_waitcnt lgkmcnt(0)
	s_barrier
	s_setprio 1
	s_waitcnt lgkmcnt(0)
	v_mfma_f32_16x16x32_bf16 v[60:63], v[140:143], v[176:179], v[60:63]
	v_mfma_f32_16x16x32_bf16 v[56:59], v[152:155], v[176:179], v[56:59]
	v_mfma_f32_16x16x32_bf16 v[52:55], v[140:143], v[202:205], v[52:55]
	v_mfma_f32_16x16x32_bf16 v[48:51], v[152:155], v[202:205], v[48:51]
	v_mfma_f32_16x16x32_bf16 v[28:31], v[140:143], v[210:213], v[28:31]
	v_mfma_f32_16x16x32_bf16 v[24:27], v[152:155], v[210:213], v[24:27]
	v_mfma_f32_16x16x32_bf16 v[16:19], v[140:143], v[218:221], v[16:19]
	v_mfma_f32_16x16x32_bf16 v[8:11], v[152:155], v[218:221], v[8:11]
	v_mfma_f32_16x16x32_bf16 v[60:63], v[144:147], v[180:183], v[60:63]
	v_mfma_f32_16x16x32_bf16 v[56:59], v[156:159], v[180:183], v[56:59]
	v_mfma_f32_16x16x32_bf16 v[52:55], v[144:147], v[206:209], v[52:55]
	v_mfma_f32_16x16x32_bf16 v[48:51], v[156:159], v[206:209], v[48:51]
	v_mfma_f32_16x16x32_bf16 v[28:31], v[144:147], v[214:217], v[28:31]
	v_mfma_f32_16x16x32_bf16 v[24:27], v[156:159], v[214:217], v[24:27]
	v_mfma_f32_16x16x32_bf16 v[16:19], v[144:147], v[222:225], v[16:19]
	v_mfma_f32_16x16x32_bf16 v[8:11], v[156:159], v[222:225], v[8:11]
	v_mfma_f32_16x16x32_bf16 v[44:47], v[160:163], v[176:179], v[44:47]
	v_mfma_f32_16x16x32_bf16 v[40:43], v[168:171], v[176:179], v[40:43]
	v_mfma_f32_16x16x32_bf16 v[36:39], v[160:163], v[202:205], v[36:39]
	v_mfma_f32_16x16x32_bf16 v[32:35], v[168:171], v[202:205], v[32:35]
	v_mfma_f32_16x16x32_bf16 v[20:23], v[160:163], v[210:213], v[20:23]
	v_mfma_f32_16x16x32_bf16 v[12:15], v[168:171], v[210:213], v[12:15]
	v_mfma_f32_16x16x32_bf16 v[4:7], v[160:163], v[218:221], v[4:7]
	v_mfma_f32_16x16x32_bf16 v[0:3], v[168:171], v[218:221], v[0:3]
	v_mfma_f32_16x16x32_bf16 v[44:47], v[164:167], v[180:183], v[44:47]
	v_mfma_f32_16x16x32_bf16 v[40:43], v[172:175], v[180:183], v[40:43]
	v_mfma_f32_16x16x32_bf16 v[36:39], v[164:167], v[206:209], v[36:39]
	v_mfma_f32_16x16x32_bf16 v[32:35], v[172:175], v[206:209], v[32:35]
	v_mfma_f32_16x16x32_bf16 v[20:23], v[164:167], v[214:217], v[20:23]
	v_mfma_f32_16x16x32_bf16 v[12:15], v[172:175], v[214:217], v[12:15]
	v_mfma_f32_16x16x32_bf16 v[4:7], v[164:167], v[222:225], v[4:7]
	v_mfma_f32_16x16x32_bf16 v[0:3], v[172:175], v[222:225], v[0:3]
	s_setprio 0
	s_barrier
	ds_read_b128 v[140:143], v186 offset:32768
	ds_read_b128 v[144:147], v186 offset:33792
	ds_read_b128 v[152:155], v186 offset:34816
	ds_read_b128 v[156:159], v186 offset:35840
	ds_read_b128 v[160:163], v186 offset:49152
	ds_read_b128 v[164:167], v186 offset:50176
	ds_read_b128 v[168:171], v186 offset:51200
	ds_read_b128 v[172:175], v186 offset:52224
	s_add_u32 s20, s38, 0xb0000
	s_addc_u32 s21, s39, 0
	s_mov_b32 m0, s47
	ds_read_b128 v[176:179], v151 offset:32768
	ds_read_b128 v[180:183], v151 offset:33792
	ds_read_b128 v[202:205], v151 offset:34816
	ds_read_b128 v[206:209], v151 offset:35840
	ds_read_b128 v[210:213], v151 offset:36864
	ds_read_b128 v[214:217], v151 offset:37888
	ds_read_b128 v[218:221], v151 offset:38912
	ds_read_b128 v[222:225], v151 offset:39936
	global_load_lds_dwordx4 v128, s[20:21]
	s_mov_b32 m0, s48
	s_nop 0
	global_load_lds_dwordx4 v132, s[20:21]
	s_waitcnt vmcnt(8)
	s_waitcnt lgkmcnt(0)
	s_barrier
; #define PG8_STAGE(bufoff, gbase, voff) do { _Pragma("unroll") for (int _i = 0; _i < 2; ++_i) \
;         __builtin_amdgcn_global_load_lds((const unsigned*)((const char*)(gbase) + (voff)[_i]), (LAS unsigned*)(lds + (bufoff) + ldsw + _i * 8192), 16, 0, 0); } while (0)
; #define PG8_LDA(dst, b, h) do { _Pragma("unroll") for (int m = 0; m < 4; ++m) _Pragma("unroll") for (int k = 0; k < 2; ++k) dst[m][k] = *(const LAS bf16x8*)(lds + PG8_SA(b, h) + aoff + m * 2048 + k * 1024); } while (0)
; #define PG8_MMA(ai, bj, At, Bt) do { __builtin_amdgcn_s_setprio(1); _Pragma("unroll") for (int m = 0; m < 4; ++m) _Pragma("unroll") for (int n = 0; n < 2; ++n) _Pragma("unroll") for (int k = 0; k < 2; ++k) \
;         acc[ai][bj][m][n] = __builtin_amdgcn_mfma_f32_16x16x32_bf16(Bt[n][k], At[m][k], acc[ai][bj][m][n], 0, 0, 0); __builtin_amdgcn_s_setprio(0); } while (0)
; #define PG8_WAIT_V(n) asm volatile("s_waitcnt vmcnt(" #n ")" ::: "memory")
; #define PG8_WAIT_L(n) asm volatile("s_waitcnt lgkmcnt(" #n ")" ::: "memory")
; #define PG8_BAR __builtin_amdgcn_s_barrier()
; #define PG8_SCHED __builtin_amdgcn_sched_barrier(0)
; template <class Epi>
; __device__ __forceinline__ void gemm_phase(LAS unsigned char* lds, const Gemm g, const Epi& E) {
;     ...
;             PG8_WAIT_V(8); PG8_WAIT_L(0); PG8_BAR; PG8_MMA(0, 0, At, B0); PG8_MMA(0, 1, At, B1); PG8_BAR; PG8_SCHED;
;             PG8_LDA(At, 1, 1); PG8_STAGE(PG8_SB(1, 0), b3, voffB); PG8_STAGE(PG8_SB(1, 1), b3 + hstepB, voffB); PG8_STAGE(PG8_SA(1, 0), a3, voffA);
;             PG8_WAIT_V(8); PG8_WAIT_L(0); PG8_BAR; PG8_MMA(1, 0, At, B0); PG8_MMA(1, 1, At, B1); PG8_BAR; PG8_SCHED;
;         }
	s_setprio 1
	s_waitcnt lgkmcnt(0)
	v_mfma_f32_16x16x32_bf16 v[124:127], v[140:143], v[176:179], v[124:127]
	v_mfma_f32_16x16x32_bf16 v[120:123], v[152:155], v[176:179], v[120:123]
	v_mfma_f32_16x16x32_bf16 v[116:119], v[140:143], v[202:205], v[116:119]
	v_mfma_f32_16x16x32_bf16 v[112:115], v[152:155], v[202:205], v[112:115]
	v_mfma_f32_16x16x32_bf16 v[92:95], v[140:143], v[210:213], v[92:95]
	v_mfma_f32_16x16x32_bf16 v[88:91], v[152:155], v[210:213], v[88:91]
	v_mfma_f32_16x16x32_bf16 v[84:87], v[140:143], v[218:221], v[84:87]
	v_mfma_f32_16x16x32_bf16 v[80:83], v[152:155], v[218:221], v[80:83]
	v_mfma_f32_16x16x32_bf16 v[124:127], v[144:147], v[180:183], v[124:127]
	v_mfma_f32_16x16x32_bf16 v[120:123], v[156:159], v[180:183], v[120:123]
	v_mfma_f32_16x16x32_bf16 v[116:119], v[144:147], v[206:209], v[116:119]
	v_mfma_f32_16x16x32_bf16 v[112:115], v[156:159], v[206:209], v[112:115]
	v_mfma_f32_16x16x32_bf16 v[92:95], v[144:147], v[214:217], v[92:95]
	v_mfma_f32_16x16x32_bf16 v[88:91], v[156:159], v[214:217], v[88:91]
	v_mfma_f32_16x16x32_bf16 v[84:87], v[144:147], v[222:225], v[84:87]
	v_mfma_f32_16x16x32_bf16 v[80:83], v[156:159], v[222:225], v[80:83]
	v_mfma_f32_16x16x32_bf16 v[108:111], v[160:163], v[176:179], v[108:111]
	v_mfma_f32_16x16x32_bf16 v[104:107], v[168:171], v[176:179], v[104:107]
	v_mfma_f32_16x16x32_bf16 v[100:103], v[160:163], v[202:205], v[100:103]
	v_mfma_f32_16x16x32_bf16 v[96:99], v[168:171], v[202:205], v[96:99]
	v_mfma_f32_16x16x32_bf16 v[76:79], v[160:163], v[210:213], v[76:79]
	v_mfma_f32_16x16x32_bf16 v[72:75], v[168:171], v[210:213], v[72:75]
	v_mfma_f32_16x16x32_bf16 v[68:71], v[160:163], v[218:221], v[68:71]
	v_mfma_f32_16x16x32_bf16 v[64:67], v[168:171], v[218:221], v[64:67]
	v_mfma_f32_16x16x32_bf16 v[108:111], v[164:167], v[180:183], v[108:111]
	v_mfma_f32_16x16x32_bf16 v[104:107], v[172:175], v[180:183], v[104:107]
	v_mfma_f32_16x16x32_bf16 v[100:103], v[164:167], v[206:209], v[100:103]
	v_mfma_f32_16x16x32_bf16 v[96:99], v[172:175], v[206:209], v[96:99]
	v_mfma_f32_16x16x32_bf16 v[76:79], v[164:167], v[214:217], v[76:79]
	v_mfma_f32_16x16x32_bf16 v[72:75], v[172:175], v[214:217], v[72:75]
	v_mfma_f32_16x16x32_bf16 v[68:71], v[164:167], v[222:225], v[68:71]
	v_mfma_f32_16x16x32_bf16 v[64:67], v[172:175], v[222:225], v[64:67]
	s_setprio 0
	s_barrier
	s_add_i32 s24, s44, 0x18000
	s_add_u32 s20, s36, 0x80
	s_addc_u32 s21, s37, 0
	s_mov_b32 m0, s24
	ds_read_b128 v[176:179], v151 offset:49152
	ds_read_b128 v[180:183], v151 offset:50176
	ds_read_b128 v[202:205], v151 offset:51200
	ds_read_b128 v[206:209], v151 offset:52224
	ds_read_b128 v[210:213], v151 offset:53248
	ds_read_b128 v[214:217], v151 offset:54272
	ds_read_b128 v[218:221], v151 offset:55296
	ds_read_b128 v[222:225], v151 offset:56320
	global_load_lds_dwordx4 v130, s[20:21]
	s_add_i32 m0, s24, 0x2000
	s_add_i32 s24, s44, 0x1c000
	global_load_lds_dwordx4 v134, s[20:21]
	s_add_u32 s20, s36, 0xb0080
	s_addc_u32 s21, s37, 0
	s_mov_b32 m0, s24
	s_nop 0
	global_load_lds_dwordx4 v130, s[20:21]
	s_add_i32 m0, s24, 0x2000
	s_nop 0
	global_load_lds_dwordx4 v134, s[20:21]
	s_add_u32 s20, s38, 0x80
	s_addc_u32 s21, s39, 0
	s_mov_b32 m0, s54
	s_nop 0
	global_load_lds_dwordx4 v128, s[20:21]
	s_mov_b32 m0, s55
	s_nop 0
	global_load_lds_dwordx4 v132, s[20:21]
	s_waitcnt vmcnt(8)
	s_waitcnt lgkmcnt(0)
	s_barrier
	s_setprio 1
	s_waitcnt lgkmcnt(0)
	v_mfma_f32_16x16x32_bf16 v[60:63], v[140:143], v[176:179], v[60:63]
	v_mfma_f32_16x16x32_bf16 v[56:59], v[152:155], v[176:179], v[56:59]
	v_mfma_f32_16x16x32_bf16 v[52:55], v[140:143], v[202:205], v[52:55]
	v_mfma_f32_16x16x32_bf16 v[48:51], v[152:155], v[202:205], v[48:51]
	v_mfma_f32_16x16x32_bf16 v[28:31], v[140:143], v[210:213], v[28:31]
	v_mfma_f32_16x16x32_bf16 v[24:27], v[152:155], v[210:213], v[24:27]
	v_mfma_f32_16x16x32_bf16 v[16:19], v[140:143], v[218:221], v[16:19]
	v_mfma_f32_16x16x32_bf16 v[8:11], v[152:155], v[218:221], v[8:11]
	v_mfma_f32_16x16x32_bf16 v[60:63], v[144:147], v[180:183], v[60:63]
	v_mfma_f32_16x16x32_bf16 v[56:59], v[156:159], v[180:183], v[56:59]
	v_mfma_f32_16x16x32_bf16 v[52:55], v[144:147], v[206:209], v[52:55]
	v_mfma_f32_16x16x32_bf16 v[48:51], v[156:159], v[206:209], v[48:51]
	v_mfma_f32_16x16x32_bf16 v[28:31], v[144:147], v[214:217], v[28:31]
	v_mfma_f32_16x16x32_bf16 v[24:27], v[156:159], v[214:217], v[24:27]
	v_mfma_f32_16x16x32_bf16 v[16:19], v[144:147], v[222:225], v[16:19]
	v_mfma_f32_16x16x32_bf16 v[8:11], v[156:159], v[222:225], v[8:11]
	v_mfma_f32_16x16x32_bf16 v[44:47], v[160:163], v[176:179], v[44:47]
	v_mfma_f32_16x16x32_bf16 v[40:43], v[168:171], v[176:179], v[40:43]
	v_mfma_f32_16x16x32_bf16 v[36:39], v[160:163], v[202:205], v[36:39]
	v_mfma_f32_16x16x32_bf16 v[32:35], v[168:171], v[202:205], v[32:35]
	v_mfma_f32_16x16x32_bf16 v[20:23], v[160:163], v[210:213], v[20:23]
	v_mfma_f32_16x16x32_bf16 v[12:15], v[168:171], v[210:213], v[12:15]
	v_mfma_f32_16x16x32_bf16 v[4:7], v[160:163], v[218:221], v[4:7]
	v_mfma_f32_16x16x32_bf16 v[0:3], v[168:171], v[218:221], v[0:3]
	v_mfma_f32_16x16x32_bf16 v[44:47], v[164:167], v[180:183], v[44:47]
	v_mfma_f32_16x16x32_bf16 v[40:43], v[172:175], v[180:183], v[40:43]
	v_mfma_f32_16x16x32_bf16 v[36:39], v[164:167], v[206:209], v[36:39]
	v_mfma_f32_16x16x32_bf16 v[32:35], v[172:175], v[206:209], v[32:35]
	v_mfma_f32_16x16x32_bf16 v[20:23], v[164:167], v[214:217], v[20:23]
	v_mfma_f32_16x16x32_bf16 v[12:15], v[172:175], v[214:217], v[12:15]
	v_mfma_f32_16x16x32_bf16 v[4:7], v[164:167], v[222:225], v[4:7]
	v_mfma_f32_16x16x32_bf16 v[0:3], v[172:175], v[222:225], v[0:3]
	s_setprio 0
	s_barrier
	s_add_i32 s42, s42, 2
	s_add_u32 s12, s12, 0x100
	s_addc_u32 s13, s13, 0
	s_cmp_gt_u32 s42, 41
	s_mov_b64 s[20:21], s[22:23]
	s_cbranch_scc0 .LBB0_547
	s_and_b64 vcc, exec, s[28:29]
	s_cbranch_vccz .LBB0_550
	s_barrier

; __global__ void __launch_bounds__(NTHR, 2) mega(Params Pval, int ph0, int ph1) {
;     ...
;         if (ph + 1 < ph1) { if (ph == 0) cg::this_grid().sync();
;             else xcd_barrier((unsigned*)(P->ws + OFF_BAR), xb_x, xb_st); }
.LBB0_902:
	s_add_i32 s0, s52, 1
	s_cmp_ge_i32 s0, s53
	s_cbranch_scc1 .Lskip_gridbar
	s_cmp_eq_u32 s52, 22
	s_cbranch_scc0 .LBB0_903
.Lskip_gridbar:
	s_getpc_b64 s[98:99]
